# one static s_setprio raise for waves 4-7 during dilated-attention items (reset at the item return)
# baseline (speedup 1.0000x reference)
.LBB0_268:
	s_and_b64 vcc, exec, s[4:5]
	s_cbranch_vccz .LBB0_295
	s_bfe_u32 s4, s20, 0x30004
	v_mov_b32_e32 v2, v254
	s_add_i32 s5, s4, 1
	v_cvt_f32_ubyte0_e32 v0, s5
	v_lshlrev_b32_e32 v5, 1, v2
	v_lshrrev_b32_e32 v6, 1, v2
	s_lshr_b32 s24, s20, 7
	v_exp_f32_e64 v3, -v0
	v_and_b32_e32 v0, 7, v2
	v_and_b32_e32 v1, 19, v2
	v_and_b32_e32 v5, 8, v5
	v_and_b32_e32 v7, 4, v6
	v_lshrrev_b32_e32 v9, 2, v2
	v_readfirstlane_b32 s8, v2
	s_lshl_b32 s5, s24, 23
	s_lshl_b32 s4, s4, 20
	v_or3_b32 v5, v7, v1, v5
	v_bitop3_b32 v1, v9, v0, 4 bitop3:0x6c
	s_ashr_i32 s9, s8, 6
	s_cmp_lt_u32 s9, 4
	s_cbranch_scc1 .Ldp_skip
	s_setprio 1
.Ldp_skip:
	s_lshr_b32 s25, s20, 4
	s_lshl_b32 s6, s20, 9
	s_or_b32 s20, s4, s5
	v_bfe_u32 v202, v2, 3, 3
	v_lshlrev_b32_e32 v10, 4, v1
	v_lshlrev_b32_e32 v1, 4, v2
	s_add_u32 s4, s57, s20
	v_and_b32_e32 v13, 0x70, v1
	v_or_b32_e32 v1, 8, v202
	s_addc_u32 s5, s58, 0
	s_lshl_b32 s7, s9, 13
	v_lshlrev_b32_e32 v14, 7, v1
	v_lshrrev_b32_e32 v1, 1, v1
	s_add_i32 s7, s7, 0x10800
	v_xor_b32_e32 v1, v1, v2
	s_cmp_lt_i32 s9, 7
	v_lshlrev_b32_e32 v1, 4, v1
	s_cselect_b32 s7, s7, 0x21000
	v_and_b32_e32 v15, 0x70, v1
	v_or_b32_e32 v1, 24, v202
	s_add_i32 s26, s7, 0
	v_lshlrev_b32_e32 v16, 7, v1
	v_lshrrev_b32_e32 v1, 1, v1
	s_and_b32 s69, s6, 0x1e00
	v_bfe_u32 v201, v2, 5, 1
	v_xor_b32_e32 v1, v1, v2
	s_add_u32 s6, s49, s20
	v_and_b32_e32 v4, 63, v2
	v_and_b32_e32 v200, 31, v2
	v_lshlrev_b32_e32 v130, 3, v201
	v_and_b32_e32 v12, 48, v2
	v_lshlrev_b32_e32 v1, 4, v1
	s_addc_u32 s7, s50, 0
	v_lshrrev_b32_e32 v18, 3, v2
	v_bfe_u32 v19, v2, 1, 1
	v_lshlrev_b32_e32 v2, 3, v2
	v_and_b32_e32 v17, 0x70, v1
	s_add_u32 s22, s51, s20
	v_lshlrev_b32_e32 v0, 4, v0
	v_mov_b32_e32 v1, v131
	v_and_or_b32 v9, v9, 3, v130
	v_and_b32_e32 v2, 8, v2
	v_lshrrev_b32_e32 v8, 1, v5
	s_addc_u32 s23, s56, 0
	v_and_or_b32 v18, v18, 2, v19
	v_lshl_or_b32 v9, v9, 7, v2
	v_mul_f32_e32 v203, 0x3fb8aa3b, v3
	v_lshlrev_b32_e32 v2, 4, v201
	v_mov_b32_e32 v3, v131
	v_lshl_add_u64 v[184:185], s[4:5], 0, v[0:1]
	s_ashr_i32 s5, s8, 2
	v_or_b32_e32 v206, 2, v201
	v_or_b32_e32 v207, 4, v201
	v_or_b32_e32 v208, 6, v201
	v_lshlrev_b32_e32 v11, 7, v202
	v_lshl_add_u64 v[128:129], s[22:23], 0, v[0:1]
	v_or_b32_e32 v7, v18, v7
	v_bitop3_b32 v6, v18, v6, 4 bitop3:0x72
	v_lshl_add_u64 v[182:183], s[6:7], 0, v[2:3]
	v_lshl_add_u32 v0, v5, 7, s26
	s_lshr_b32 s4, s69, 2
	s_and_b32 s73, s5, 0xffffffc0
	v_xad_u32 v1, v13, v12, s26
	v_add_u32_e32 v3, s26, v15
	v_add_u32_e32 v5, s26, v17
	v_bitop3_b32 v13, v8, v201, 7 bitop3:0x6c
	v_bitop3_b32 v15, v8, v206, 7 bitop3:0x6c
	v_bitop3_b32 v17, v8, v207, 7 bitop3:0x6c
	v_bitop3_b32 v8, v8, v208, 7 bitop3:0x6c
	s_add_i32 s73, s73, s4
	s_and_b32 s74, s8, 0xffffffc0
	s_lshl_b32 s6, s25, 6
	v_cmp_gt_u32_e64 s[4:5], 32, v4
	v_add_u32_e32 v2, s26, v11
	v_add_u32_e32 v4, s26, v14
	v_add_u32_e32 v12, s26, v16
	v_lshlrev_b32_e32 v13, 4, v13
	v_lshlrev_b32_e32 v15, 4, v15
	v_lshlrev_b32_e32 v17, 4, v17
	v_lshlrev_b32_e32 v8, 4, v8
	v_lshl_add_u32 v7, v7, 4, s26
	v_lshl_add_u32 v6, v6, 4, s26
	v_or_b32_e32 v204, 32, v200
	v_or_b32_e32 v205, 0xffffffc0, v202
	s_add_i32 s70, s9, -16
	s_and_b32 s71, s9, 3
	s_lshr_b32 s72, s69, 4
	s_add_i32 s74, s74, s69
	s_lshl_b32 s20, s24, 13
	v_or_b32_e32 v209, 8, v201
	v_or_b32_e32 v210, 10, v201
	v_or_b32_e32 v211, 12, v201
	v_or_b32_e32 v212, 14, v201
	s_or_b32 s22, s6, 0x200
	s_mov_b32 s23, s21
	v_lshl_add_u64 v[186:187], s[16:17], 0, v[130:131]
	v_lshl_add_u64 v[188:189], s[18:19], 0, v[130:131]
	v_sub_u32_e32 v130, v130, v200
	s_mov_b32 s75, 0
	v_add_u32_e32 v213, v1, v11
	v_add_u32_e32 v214, v2, v10
	v_add_u32_e32 v215, v3, v14
	v_add_u32_e32 v216, v4, v10
	v_add_u32_e32 v217, v5, v16
	v_add_u32_e32 v218, v12, v10
	v_add_u32_e32 v219, v0, v13
	v_add_u32_e32 v220, v0, v15
	v_add_u32_e32 v221, v0, v17
	v_add_u32_e32 v222, v0, v8
	v_add_u32_e32 v223, v7, v9
	v_add_u32_e32 v224, v6, v9
	s_branch .LBB0_271
